# v19 + in_proj tile schedule: third column tile swapped between the two workgroup groups -> (q,v,z_ssm)/(k,z_attn,u)
# speedup vs baseline: 1.0144x; 1.0050x over previous
;     __device__ bool next(int i, Unit& u) const { const int L = i * G + c; if (L >= 128) return false; u.pm = L; u.pn = L >> 2; return true; }
;     __device__ bool next(int i, Unit& u) const { if (i) return false; u.pm = pm; u.pn = pn; return true; }
;     __device__ bool next(int i, Unit& u) const {
;         const int L = i * G + c; if (L >= nwg) return false;
;         int wgid = L; { constexpr int q = nwg / NXCD, r = nwg % NXCD; const int xcd = wgid % NXCD, off = wgid / NXCD; wgid = (xcd < r ? xcd * (q + 1) : r * (q + 1) + (xcd - r) * q) + off; }
;         constexpr int nig = WGM * nN; const int gid = wgid / nig, fm = gid * WGM, gsz = (nM - fm) < WGM ? (nM - fm) : WGM;
;         u.pm = fm + ((wgid % nig) % gsz); u.pn = (wgid % nig) / gsz; return true;
.LBB0_186:
	s_add_i32 s50, s50, 1
	s_lshl_b32 s27, s50, 8
	s_add_i32 s27, s27, s2
	s_cmpk_lt_i32 s27, 0x300
	s_cselect_b64 s[30:31], -1, 0
	s_cmpk_gt_i32 s27, 0x2ff
	s_cbranch_scc1 .LBB0_188
	s_ashr_i32 s26, s27, 31
	s_lshr_b32 s26, s26, 29
	s_add_i32 s26, s27, s26
	s_ashr_i32 s28, s26, 3
	s_and_b32 s26, s26, -8
	s_sub_i32 s26, s27, s26
	s_cmp_lt_i32 s26, 0
	s_cselect_b32 s27, s56, 0x60
	s_mul_i32 s26, s27, s26
	s_add_i32 s26, s26, s28
	s_mul_hi_i32 s27, s26, 0x2aaaaaab
	s_lshr_b32 s28, s27, 31
	s_ashr_i32 s27, s27, 4
	s_add_i32 s27, s27, s28
	s_lshl_b32 s28, s27, 3
	s_mulk_i32 s27, 0x60
	s_sub_i32 s26, s26, s27
	s_bfe_i32 s27, s26, 0x80000
	s_bfe_u32 s27, s27, 0x3000c
	s_add_i32 s27, s26, s27
	s_bfe_i32 s29, s27, 0x80000
	s_and_b32 s27, s27, 0xf8
	s_sub_i32 s26, s26, s27
	s_sext_i32_i16 s29, s29
	s_sext_i32_i8 s26, s26
	s_add_i32 s26, s28, s26
	s_ashr_i32 s28, s29, 3
	s_cmp_eq_u32 s50, 2
	s_cselect_b32 s98, 2, 0
	s_xor_b32 s28, s28, s98
